# final rmsnorm rewritten as two-set pipelined loop (plus phase-0 rmsnorm prefetch)
# baseline (speedup 1.0000x reference)
; DI int bidx() { int b = blockIdx.x; asm volatile("" : "+s"(b)); return b; }
; DI const float* IN(int i) { return *(const float* const __attribute__((address_space(4)))*)(KA() + 8 * i); }
; DI float* OUTP() { return *(float* const __attribute__((address_space(4)))*)(KA() + 8 * 29); }
; DI void rmsnorm_rows(const float* x, const float* g, bf16_t* outb, float* outf) {
;     ...
;   for (int it = bidx(); it < NTOK / 16; it += gridDim.x) {
;     float4 v[2][4]; float ss[2] = {0.f, 0.f};
; #pragma unroll
;     for (int rr = 0; rr < 2; ++rr) {
;       const float* xr = x + (size_t)(it * 16 + rr * 8 + w) * 1024;
; #pragma unroll
;       for (int i = 0; i < 4; ++i) v[rr][i] = *(const float4*)(xr + lane * 4 + 256 * i);
;     }
;     float4 gg[4];
; #pragma unroll
;     for (int i = 0; i < 4; ++i) gg[i] = *(const float4*)(g + lane * 4 + 256 * i);
; __global__ void __launch_bounds__(512, 2) fwd_megakernel(Params p) {
;     ...
;   rmsnorm_rows(OUTP(), IN(28), nullptr, OUTP());
.LBB0_1090:
	v_readlane_b32 s4, v252, 45
	global_load_dwordx4 v[188:191], v[50:51], off
	global_load_dwordx4 v[184:187], v[50:51], off offset:1024
	global_load_dwordx4 v[180:183], v[50:51], off offset:2048
	global_load_dwordx4 v[176:179], v[50:51], off offset:3072
	s_mov_b32 s2, 0x3a800000
	s_mov_b64 s[98:99], 0x8000
	v_mov_b32_e32 v195, 0
	v_lshlrev_b32_e32 v194, 12, v56
	v_lshl_add_u64 v[196:197], v[48:49], 0, v[194:195]
	global_load_dwordx4 v[14:17], v[196:197], off
	global_load_dwordx4 v[22:25], v[196:197], off offset:1024
	global_load_dwordx4 v[2:5], v[196:197], off offset:2048
	global_load_dwordx4 v[6:9], v[196:197], off offset:3072
	v_lshl_add_u64 v[198:199], v[196:197], 0, s[98:99]
	global_load_dwordx4 v[38:41], v[198:199], off
	global_load_dwordx4 v[30:33], v[198:199], off offset:1024
	global_load_dwordx4 v[26:29], v[198:199], off offset:2048
	global_load_dwordx4 v[10:13], v[198:199], off offset:3072
	v_lshl_add_u64 v[60:61], v[52:53], 0, v[194:195]
	v_lshl_add_u64 v[58:59], v[60:61], 0, s[98:99]
	v_add_u32_e32 v56, s4, v56
.Lfn_loop:
	s_add_i32 s12, s12, s8
	s_cmpk_lt_i32 s12, 0x400
	s_cbranch_scc0 .Lfn_lastA
	v_lshlrev_b32_e32 v194, 12, v56
	v_lshl_add_u64 v[196:197], v[48:49], 0, v[194:195]
	global_load_dwordx4 v[102:105], v[196:197], off
	global_load_dwordx4 v[110:113], v[196:197], off offset:1024
	global_load_dwordx4 v[90:93], v[196:197], off offset:2048
	global_load_dwordx4 v[94:97], v[196:197], off offset:3072
	v_lshl_add_u64 v[198:199], v[196:197], 0, s[98:99]
	global_load_dwordx4 v[126:129], v[198:199], off
	global_load_dwordx4 v[118:121], v[198:199], off offset:1024
	global_load_dwordx4 v[114:117], v[198:199], off offset:2048
	global_load_dwordx4 v[98:101], v[198:199], off offset:3072
	v_lshl_add_u64 v[148:149], v[52:53], 0, v[194:195]
	v_lshl_add_u64 v[146:147], v[148:149], 0, s[98:99]
	v_add_u32_e32 v56, s4, v56
	s_waitcnt vmcnt(8)
	s_branch .Lfn_compA

; DI float wave_sum_fast(float v) { v = fdpp_add(v, 0); v = fdpp_add(v, 1); v = fdpp_add(v, 2); v = fdpp_add(v, 3); v = xor16_sum(v); return xor32_sum(v); }
; DI void rmsnorm_rows(const float* x, const float* g, bf16_t* outb, float* outf) {
;     ...
;     for (int rr = 0; rr < 2; ++rr) {
; #pragma unroll
;       for (int i = 0; i < 4; ++i) ss[rr] += v[rr][i].x * v[rr][i].x + v[rr][i].y * v[rr][i].y + v[rr][i].z * v[rr][i].z + v[rr][i].w * v[rr][i].w;
;       ss[rr] = wave_sum_fast(ss[rr]);
;     }
; #pragma unroll
;     for (int rr = 0; rr < 2; ++rr) {
;       const int row = it * 16 + rr * 8 + w;
;       const float rs = rsqrtf(ss[rr] * (1.f / 1024.f) + 1e-6f);
; #pragma unroll
;       for (int i = 0; i < 4; ++i) {
;         const float o0 = v[rr][i].x * rs * gg[i].x, o1 = v[rr][i].y * rs * gg[i].y, o2 = v[rr][i].z * rs * gg[i].z, o3 = v[rr][i].w * rs * gg[i].w;
;         if (outf) { *(float4*)(outf + (size_t)row * 1024 + lane * 4 + 256 * i) = make_float4(o0, o1, o2, o3); }
.Lfn_compA:
	v_pk_mul_f32 v[64:65], v[14:15], v[14:15]
	v_pk_mul_f32 v[68:69], v[22:23], v[22:23]
	v_pk_mul_f32 v[62:63], v[16:17], v[16:17]
	v_pk_mul_f32 v[72:73], v[6:7], v[6:7]
	v_pk_mul_f32 v[66:67], v[24:25], v[24:25]
	v_pk_mul_f32 v[70:71], v[2:3], v[2:3]
	v_pk_mul_f32 v[76:77], v[8:9], v[8:9]
	v_add_f32_e32 v0, v68, v69
	v_add_f32_e32 v57, v64, v65
	v_add_f32_e32 v87, v72, v73
	v_pk_mul_f32 v[64:65], v[38:39], v[38:39]
	v_pk_mul_f32 v[68:69], v[30:31], v[30:31]
	v_add_f32_e32 v86, v70, v71
	v_pk_mul_f32 v[70:71], v[26:27], v[26:27]
	v_pk_mul_f32 v[78:79], v[40:41], v[40:41]
	v_pk_mul_f32 v[80:81], v[32:33], v[32:33]
	v_add_f32_e32 v68, v68, v69
	v_add_f32_e32 v64, v64, v65
	v_add_f32_e32 v0, v0, v66
	v_add_f32_e32 v57, v57, v62
	v_add_f32_e32 v66, v87, v76
	v_pk_mul_f32 v[74:75], v[4:5], v[4:5]
	v_pk_mul_f32 v[72:73], v[10:11], v[10:11]
	v_pk_mul_f32 v[82:83], v[28:29], v[28:29]
	v_add_f32_e32 v65, v70, v71
	v_add_f32_e32 v0, v0, v67
	v_add_f32_e32 v57, v57, v63
	v_add_f32_e32 v63, v66, v77
	v_add_f32_e32 v66, v68, v80
	v_add_f32_e32 v64, v64, v78
	v_pk_mul_f32 v[84:85], v[12:13], v[12:13]
	v_add_f32_e32 v69, v72, v73
	v_add_f32_e32 v62, v86, v74
	v_add_f32_e32 v65, v65, v82
	v_add_f32_e32 v66, v66, v81
	v_add_f32_e32 v0, v57, v0
	v_add_f32_e32 v57, v64, v79
	v_add_f32_e32 v62, v62, v75
	v_add_f32_e32 v67, v69, v84
	v_add_f32_e32 v64, v65, v83
	v_add_f32_e32 v57, v57, v66
	v_add_f32_e32 v65, v67, v85
	v_add_f32_e32 v0, v0, v62
	v_add_f32_e32 v57, v57, v64
	v_add_f32_e32 v0, v0, v63
	v_add_f32_e32 v57, v57, v65
	s_nop 0
	v_add_f32_dpp v0, v0, v0 quad_perm:[1,0,3,2] row_mask:0xf bank_mask:0xf bound_ctrl:1
	v_add_f32_dpp v57, v57, v57 quad_perm:[1,0,3,2] row_mask:0xf bank_mask:0xf bound_ctrl:1
	s_nop 0
	v_add_f32_dpp v0, v0, v0 quad_perm:[2,3,0,1] row_mask:0xf bank_mask:0xf bound_ctrl:1
	v_add_f32_dpp v57, v57, v57 quad_perm:[2,3,0,1] row_mask:0xf bank_mask:0xf bound_ctrl:1
	s_nop 0
	v_add_f32_dpp v0, v0, v0 row_half_mirror row_mask:0xf bank_mask:0xf bound_ctrl:1
	v_add_f32_dpp v57, v57, v57 row_half_mirror row_mask:0xf bank_mask:0xf bound_ctrl:1
	s_nop 0
	v_add_f32_dpp v0, v0, v0 row_mirror row_mask:0xf bank_mask:0xf bound_ctrl:1
	v_add_f32_dpp v57, v57, v57 row_mirror row_mask:0xf bank_mask:0xf bound_ctrl:1
	v_mov_b32_e32 v62, v0
	v_mov_b32_e32 v64, v57
	s_nop 0
	v_permlane16_swap_b32_e32 v0, v62
	v_permlane16_swap_b32_e32 v57, v64
	v_add_f32_e32 v63, v0, v62
	v_add_f32_e32 v62, v57, v64
	v_mov_b32_e32 v65, v63
	v_mov_b32_e32 v64, v62
	s_nop 0
	v_permlane32_swap_b32_e32 v63, v65
	v_permlane32_swap_b32_e32 v62, v64
	v_pk_add_f32 v[62:63], v[62:63], v[64:65]
	s_nop 0
	v_pk_fma_f32 v[62:63], v[62:63], s[2:3], v[200:201] op_sel_hi:[1,0,0]
	s_nop 0
	v_rsq_f32_e32 v0, v63
	v_rsq_f32_e32 v62, v62
	s_nop 0
	v_pk_mul_f32 v[14:15], v[14:15], v[0:1] op_sel_hi:[1,0]
	v_pk_mul_f32 v[16:17], v[16:17], v[0:1] op_sel_hi:[1,0]
	v_pk_mul_f32 v[22:23], v[22:23], v[0:1] op_sel_hi:[1,0]
	v_pk_mul_f32 v[24:25], v[24:25], v[0:1] op_sel_hi:[1,0]
	v_pk_mul_f32 v[2:3], v[2:3], v[0:1] op_sel_hi:[1,0]
	v_pk_mul_f32 v[4:5], v[4:5], v[0:1] op_sel_hi:[1,0]
	v_pk_mul_f32 v[6:7], v[6:7], v[0:1] op_sel_hi:[1,0]
	v_pk_mul_f32 v[8:9], v[8:9], v[0:1] op_sel_hi:[1,0]
	v_pk_mul_f32 v[14:15], v[188:189], v[14:15]
	v_pk_mul_f32 v[16:17], v[190:191], v[16:17]
	v_pk_mul_f32 v[22:23], v[184:185], v[22:23]
	v_pk_mul_f32 v[24:25], v[186:187], v[24:25]
	v_pk_mul_f32 v[2:3], v[180:181], v[2:3]
	v_pk_mul_f32 v[4:5], v[182:183], v[4:5]
	v_pk_mul_f32 v[6:7], v[176:177], v[6:7]
	v_pk_mul_f32 v[8:9], v[178:179], v[8:9]
	v_pk_mul_f32 v[38:39], v[38:39], v[62:63] op_sel_hi:[1,0]
	v_pk_mul_f32 v[40:41], v[40:41], v[62:63] op_sel_hi:[1,0]
	v_pk_mul_f32 v[30:31], v[30:31], v[62:63] op_sel_hi:[1,0]
	v_pk_mul_f32 v[32:33], v[32:33], v[62:63] op_sel_hi:[1,0]
	v_pk_mul_f32 v[26:27], v[26:27], v[62:63] op_sel_hi:[1,0]
	v_pk_mul_f32 v[28:29], v[28:29], v[62:63] op_sel_hi:[1,0]
	v_pk_mul_f32 v[10:11], v[10:11], v[62:63] op_sel_hi:[1,0]
	v_pk_mul_f32 v[12:13], v[12:13], v[62:63] op_sel_hi:[1,0]
	v_pk_mul_f32 v[38:39], v[188:189], v[38:39]
	v_pk_mul_f32 v[40:41], v[190:191], v[40:41]
	v_pk_mul_f32 v[30:31], v[184:185], v[30:31]
	v_pk_mul_f32 v[32:33], v[186:187], v[32:33]
	v_pk_mul_f32 v[26:27], v[180:181], v[26:27]
	v_pk_mul_f32 v[28:29], v[182:183], v[28:29]
	v_pk_mul_f32 v[10:11], v[176:177], v[10:11]
	v_pk_mul_f32 v[12:13], v[178:179], v[12:13]
	global_store_dwordx4 v[60:61], v[14:17], off
	global_store_dwordx4 v[60:61], v[22:25], off offset:1024
	global_store_dwordx4 v[60:61], v[2:5], off offset:2048
	global_store_dwordx4 v[60:61], v[6:9], off offset:3072
	global_store_dwordx4 v[58:59], v[38:41], off
	global_store_dwordx4 v[58:59], v[30:33], off offset:1024
	global_store_dwordx4 v[58:59], v[26:29], off offset:2048
	global_store_dwordx4 v[58:59], v[10:13], off offset:3072
	s_cmpk_lt_i32 s12, 0x400
	s_cbranch_scc0 .LBB0_1123
	s_add_i32 s12, s12, s8
	s_cmpk_lt_i32 s12, 0x400
	s_cbranch_scc0 .Lfn_lastB
	v_lshlrev_b32_e32 v194, 12, v56
	v_lshl_add_u64 v[196:197], v[48:49], 0, v[194:195]
	global_load_dwordx4 v[14:17], v[196:197], off
	global_load_dwordx4 v[22:25], v[196:197], off offset:1024
	global_load_dwordx4 v[2:5], v[196:197], off offset:2048
	global_load_dwordx4 v[6:9], v[196:197], off offset:3072
	v_lshl_add_u64 v[198:199], v[196:197], 0, s[98:99]
	global_load_dwordx4 v[38:41], v[198:199], off
	global_load_dwordx4 v[30:33], v[198:199], off offset:1024
	global_load_dwordx4 v[26:29], v[198:199], off offset:2048
	global_load_dwordx4 v[10:13], v[198:199], off offset:3072
	v_lshl_add_u64 v[60:61], v[52:53], 0, v[194:195]
	v_lshl_add_u64 v[58:59], v[60:61], 0, s[98:99]
	v_add_u32_e32 v56, s4, v56
	s_waitcnt vmcnt(8)
	s_branch .Lfn_compB

; DI float wave_sum_fast(float v) { v = fdpp_add(v, 0); v = fdpp_add(v, 1); v = fdpp_add(v, 2); v = fdpp_add(v, 3); v = xor16_sum(v); return xor32_sum(v); }
; DI void rmsnorm_rows(const float* x, const float* g, bf16_t* outb, float* outf) {
;     ...
;     for (int rr = 0; rr < 2; ++rr) {
; #pragma unroll
;       for (int i = 0; i < 4; ++i) ss[rr] += v[rr][i].x * v[rr][i].x + v[rr][i].y * v[rr][i].y + v[rr][i].z * v[rr][i].z + v[rr][i].w * v[rr][i].w;
;       ss[rr] = wave_sum_fast(ss[rr]);
;     }
; #pragma unroll
;     for (int rr = 0; rr < 2; ++rr) {
;       const int row = it * 16 + rr * 8 + w;
;       const float rs = rsqrtf(ss[rr] * (1.f / 1024.f) + 1e-6f);
; #pragma unroll
;       for (int i = 0; i < 4; ++i) {
;         const float o0 = v[rr][i].x * rs * gg[i].x, o1 = v[rr][i].y * rs * gg[i].y, o2 = v[rr][i].z * rs * gg[i].z, o3 = v[rr][i].w * rs * gg[i].w;
;         if (outf) { *(float4*)(outf + (size_t)row * 1024 + lane * 4 + 256 * i) = make_float4(o0, o1, o2, o3); }
.Lfn_compB:
	v_pk_mul_f32 v[64:65], v[102:103], v[102:103]
	v_pk_mul_f32 v[68:69], v[110:111], v[110:111]
	v_pk_mul_f32 v[62:63], v[104:105], v[104:105]
	v_pk_mul_f32 v[72:73], v[94:95], v[94:95]
	v_pk_mul_f32 v[66:67], v[112:113], v[112:113]
	v_pk_mul_f32 v[70:71], v[90:91], v[90:91]
	v_pk_mul_f32 v[76:77], v[96:97], v[96:97]
	v_add_f32_e32 v0, v68, v69
	v_add_f32_e32 v57, v64, v65
	v_add_f32_e32 v87, v72, v73
	v_pk_mul_f32 v[64:65], v[126:127], v[126:127]
	v_pk_mul_f32 v[68:69], v[118:119], v[118:119]
	v_add_f32_e32 v86, v70, v71
	v_pk_mul_f32 v[70:71], v[114:115], v[114:115]
	v_pk_mul_f32 v[78:79], v[128:129], v[128:129]
	v_pk_mul_f32 v[80:81], v[120:121], v[120:121]
	v_add_f32_e32 v68, v68, v69
	v_add_f32_e32 v64, v64, v65
	v_add_f32_e32 v0, v0, v66
	v_add_f32_e32 v57, v57, v62
	v_add_f32_e32 v66, v87, v76
	v_pk_mul_f32 v[74:75], v[92:93], v[92:93]
	v_pk_mul_f32 v[72:73], v[98:99], v[98:99]
	v_pk_mul_f32 v[82:83], v[116:117], v[116:117]
	v_add_f32_e32 v65, v70, v71
	v_add_f32_e32 v0, v0, v67
	v_add_f32_e32 v57, v57, v63
	v_add_f32_e32 v63, v66, v77
	v_add_f32_e32 v66, v68, v80
	v_add_f32_e32 v64, v64, v78
	v_pk_mul_f32 v[84:85], v[100:101], v[100:101]
	v_add_f32_e32 v69, v72, v73
	v_add_f32_e32 v62, v86, v74
	v_add_f32_e32 v65, v65, v82
	v_add_f32_e32 v66, v66, v81
	v_add_f32_e32 v0, v57, v0
	v_add_f32_e32 v57, v64, v79
	v_add_f32_e32 v62, v62, v75
	v_add_f32_e32 v67, v69, v84
	v_add_f32_e32 v64, v65, v83
	v_add_f32_e32 v57, v57, v66
	v_add_f32_e32 v65, v67, v85
	v_add_f32_e32 v0, v0, v62
	v_add_f32_e32 v57, v57, v64
	v_add_f32_e32 v0, v0, v63
	v_add_f32_e32 v57, v57, v65
	s_nop 0
	v_add_f32_dpp v0, v0, v0 quad_perm:[1,0,3,2] row_mask:0xf bank_mask:0xf bound_ctrl:1
	v_add_f32_dpp v57, v57, v57 quad_perm:[1,0,3,2] row_mask:0xf bank_mask:0xf bound_ctrl:1
	s_nop 0
	v_add_f32_dpp v0, v0, v0 quad_perm:[2,3,0,1] row_mask:0xf bank_mask:0xf bound_ctrl:1
	v_add_f32_dpp v57, v57, v57 quad_perm:[2,3,0,1] row_mask:0xf bank_mask:0xf bound_ctrl:1
	s_nop 0
	v_add_f32_dpp v0, v0, v0 row_half_mirror row_mask:0xf bank_mask:0xf bound_ctrl:1
	v_add_f32_dpp v57, v57, v57 row_half_mirror row_mask:0xf bank_mask:0xf bound_ctrl:1
	s_nop 0
	v_add_f32_dpp v0, v0, v0 row_mirror row_mask:0xf bank_mask:0xf bound_ctrl:1
	v_add_f32_dpp v57, v57, v57 row_mirror row_mask:0xf bank_mask:0xf bound_ctrl:1
	v_mov_b32_e32 v62, v0
	v_mov_b32_e32 v64, v57
	s_nop 0
	v_permlane16_swap_b32_e32 v0, v62
	v_permlane16_swap_b32_e32 v57, v64
	v_add_f32_e32 v63, v0, v62
	v_add_f32_e32 v62, v57, v64
	v_mov_b32_e32 v65, v63
	v_mov_b32_e32 v64, v62
	s_nop 0
	v_permlane32_swap_b32_e32 v63, v65
	v_permlane32_swap_b32_e32 v62, v64
	v_pk_add_f32 v[62:63], v[62:63], v[64:65]
	s_nop 0
	v_pk_fma_f32 v[62:63], v[62:63], s[2:3], v[200:201] op_sel_hi:[1,0,0]
	s_nop 0
	v_rsq_f32_e32 v0, v63
	v_rsq_f32_e32 v62, v62
	s_nop 0
	v_pk_mul_f32 v[102:103], v[102:103], v[0:1] op_sel_hi:[1,0]
	v_pk_mul_f32 v[104:105], v[104:105], v[0:1] op_sel_hi:[1,0]
	v_pk_mul_f32 v[110:111], v[110:111], v[0:1] op_sel_hi:[1,0]
	v_pk_mul_f32 v[112:113], v[112:113], v[0:1] op_sel_hi:[1,0]
	v_pk_mul_f32 v[90:91], v[90:91], v[0:1] op_sel_hi:[1,0]
	v_pk_mul_f32 v[92:93], v[92:93], v[0:1] op_sel_hi:[1,0]
	v_pk_mul_f32 v[94:95], v[94:95], v[0:1] op_sel_hi:[1,0]
	v_pk_mul_f32 v[96:97], v[96:97], v[0:1] op_sel_hi:[1,0]
	v_pk_mul_f32 v[102:103], v[188:189], v[102:103]
	v_pk_mul_f32 v[104:105], v[190:191], v[104:105]
	v_pk_mul_f32 v[110:111], v[184:185], v[110:111]
	v_pk_mul_f32 v[112:113], v[186:187], v[112:113]
	v_pk_mul_f32 v[90:91], v[180:181], v[90:91]
	v_pk_mul_f32 v[92:93], v[182:183], v[92:93]
	v_pk_mul_f32 v[94:95], v[176:177], v[94:95]
	v_pk_mul_f32 v[96:97], v[178:179], v[96:97]
	v_pk_mul_f32 v[126:127], v[126:127], v[62:63] op_sel_hi:[1,0]
	v_pk_mul_f32 v[128:129], v[128:129], v[62:63] op_sel_hi:[1,0]
	v_pk_mul_f32 v[118:119], v[118:119], v[62:63] op_sel_hi:[1,0]
	v_pk_mul_f32 v[120:121], v[120:121], v[62:63] op_sel_hi:[1,0]
	v_pk_mul_f32 v[114:115], v[114:115], v[62:63] op_sel_hi:[1,0]
	v_pk_mul_f32 v[116:117], v[116:117], v[62:63] op_sel_hi:[1,0]
	v_pk_mul_f32 v[98:99], v[98:99], v[62:63] op_sel_hi:[1,0]
	v_pk_mul_f32 v[100:101], v[100:101], v[62:63] op_sel_hi:[1,0]
	v_pk_mul_f32 v[126:127], v[188:189], v[126:127]
	v_pk_mul_f32 v[128:129], v[190:191], v[128:129]
	v_pk_mul_f32 v[118:119], v[184:185], v[118:119]
	v_pk_mul_f32 v[120:121], v[186:187], v[120:121]
	v_pk_mul_f32 v[114:115], v[180:181], v[114:115]
	v_pk_mul_f32 v[116:117], v[182:183], v[116:117]
	v_pk_mul_f32 v[98:99], v[176:177], v[98:99]
	v_pk_mul_f32 v[100:101], v[178:179], v[100:101]
	global_store_dwordx4 v[148:149], v[102:105], off
	global_store_dwordx4 v[148:149], v[110:113], off offset:1024
	global_store_dwordx4 v[148:149], v[90:93], off offset:2048
	global_store_dwordx4 v[148:149], v[94:97], off offset:3072
	global_store_dwordx4 v[146:147], v[126:129], off
	global_store_dwordx4 v[146:147], v[118:121], off offset:1024
	global_store_dwordx4 v[146:147], v[114:117], off offset:2048
	global_store_dwordx4 v[146:147], v[98:101], off offset:3072
	s_cmpk_lt_i32 s12, 0x400
	s_cbranch_scc1 .Lfn_loop
